# P1 silu-mode epilogue copy: the vmcnt(0) that only guarded the k-gate mode's loads removed (it stalled on the next tile's prefetch DMAs)
# speedup vs baseline: 1.0086x; 1.0086x over previous
.Lsig_m1:
	v_ashrrev_i32_e32 v0, 31, v202
	v_mul_lo_u32 v174, s57, v202
	v_mul_lo_u32 v0, s56, v0
	v_mad_u64_u32 v[176:177], s[10:11], s56, v202, 0
	v_add3_u32 v177, v177, v0, v174
	v_pk_mul_f32 v[174:175], v[128:129], s[8:9] op_sel_hi:[1,0]
	v_pk_mul_f32 v[204:205], v[126:127], s[8:9] op_sel_hi:[1,0]
	v_min_f32_e32 v174, 0x41e6d4ca, v174
	v_min_f32_e32 v203, 0x41e6d4ca, v204
	v_exp_f32_e32 v207, v203
	v_min_f32_e32 v203, 0x41e6d4ca, v205
	v_exp_f32_e32 v205, v174
	v_min_f32_e32 v174, 0x41e6d4ca, v175
	v_exp_f32_e32 v206, v203
	v_exp_f32_e32 v204, v174
	v_pk_add_f32 v[174:175], v[206:207], 1.0 op_sel_hi:[1,0]
	v_pk_add_f32 v[204:205], v[204:205], 1.0 op_sel_hi:[1,0]
	v_mul_f32_e32 v206, v175, v174
	v_mul_f32_e32 v207, v205, v204
	s_nop 0
	v_mul_f32_e32 v203, v206, v207
	v_rcp_f32_e32 v203, v203
	s_nop 0
	v_mul_f32_e32 v208, v207, v203
	v_mul_f32_e32 v206, v206, v203
	v_pk_mul_f32 v[174:175], v[174:175], v[208:209] op_sel_hi:[1,0]
	v_pk_mul_f32 v[204:205], v[204:205], v[206:207] op_sel_hi:[1,0]
	v_pk_mul_f32 v[174:175], v[126:127], v[174:175]
	v_pk_mul_f32 v[206:207], v[122:123], s[8:9] op_sel_hi:[1,0]
	s_nop 0
	v_min_f32_e32 v203, 0x41e6d4ca, v206
	v_pk_mul_f32 v[208:209], v[128:129], v[204:205]
	v_pk_mul_f32 v[204:205], v[124:125], s[8:9] op_sel_hi:[1,0]
	v_exp_f32_e32 v211, v203
	v_min_f32_e32 v203, 0x41e6d4ca, v207
	v_exp_f32_e32 v210, v203
	v_min_f32_e32 v203, 0x41e6d4ca, v204
	v_exp_f32_e32 v207, v203
	v_min_f32_e32 v203, 0x41e6d4ca, v205
	v_exp_f32_e32 v206, v203
	v_pk_add_f32 v[204:205], v[210:211], 1.0 op_sel_hi:[1,0]
	v_pk_add_f32 v[206:207], v[206:207], 1.0 op_sel_hi:[1,0]
	v_mul_f32_e32 v210, v205, v204
	v_mul_f32_e32 v211, v207, v206
	s_nop 0
	v_mul_f32_e32 v203, v210, v211
	v_rcp_f32_e32 v203, v203
	s_nop 0
	v_mul_f32_e32 v212, v211, v203
	v_mul_f32_e32 v210, v210, v203
	v_pk_mul_f32 v[204:205], v[204:205], v[212:213] op_sel_hi:[1,0]
	v_pk_mul_f32 v[206:207], v[206:207], v[210:211] op_sel_hi:[1,0]
	v_pk_mul_f32 v[212:213], v[124:125], v[206:207]
	v_pk_mul_f32 v[206:207], v[122:123], v[204:205]
	v_cvt_pk_bf16_f32 v204, v174, v175
	v_cvt_pk_bf16_f32 v205, v208, v209
	v_lshl_add_u64 v[174:175], v[170:171], 1, s[86:87]
	v_lshlrev_b64 v[208:209], 1, v[176:177]
	v_cvt_pk_bf16_f32 v206, v206, v207
	v_cvt_pk_bf16_f32 v207, v212, v213
	v_lshl_add_u64 v[176:177], v[174:175], 0, v[208:209]
	global_store_dwordx4 v[176:177], v[204:207], off
	v_pk_mul_f32 v[176:177], v[120:121], s[8:9] op_sel_hi:[1,0]
	s_nop 0
	v_pk_mul_f32 v[204:205], v[118:119], s[8:9] op_sel_hi:[1,0]
	v_min_f32_e32 v176, 0x41e6d4ca, v176
	v_min_f32_e32 v203, 0x41e6d4ca, v204
	v_exp_f32_e32 v207, v203
	v_min_f32_e32 v203, 0x41e6d4ca, v205
	v_exp_f32_e32 v205, v176
	v_min_f32_e32 v176, 0x41e6d4ca, v177
	v_exp_f32_e32 v206, v203
	v_exp_f32_e32 v204, v176
	v_pk_add_f32 v[176:177], v[206:207], 1.0 op_sel_hi:[1,0]
	v_pk_add_f32 v[204:205], v[204:205], 1.0 op_sel_hi:[1,0]
	v_mul_f32_e32 v206, v177, v176
	v_mul_f32_e32 v207, v205, v204
	s_nop 0
	v_mul_f32_e32 v203, v206, v207
	v_rcp_f32_e32 v203, v203
	s_nop 0
	v_mul_f32_e32 v210, v207, v203
	v_mul_f32_e32 v206, v206, v203
	v_pk_mul_f32 v[176:177], v[176:177], v[210:211] op_sel_hi:[1,0]
	v_pk_mul_f32 v[204:205], v[204:205], v[206:207] op_sel_hi:[1,0]
	v_pk_mul_f32 v[176:177], v[118:119], v[176:177]
	v_pk_mul_f32 v[206:207], v[114:115], s[8:9] op_sel_hi:[1,0]
	s_nop 0
	v_min_f32_e32 v203, 0x41e6d4ca, v206
	v_pk_mul_f32 v[210:211], v[120:121], v[204:205]
	v_pk_mul_f32 v[204:205], v[116:117], s[8:9] op_sel_hi:[1,0]
	v_exp_f32_e32 v213, v203
	v_min_f32_e32 v203, 0x41e6d4ca, v207
	v_exp_f32_e32 v212, v203
	v_min_f32_e32 v203, 0x41e6d4ca, v204
	v_exp_f32_e32 v207, v203
	v_min_f32_e32 v203, 0x41e6d4ca, v205
	v_exp_f32_e32 v206, v203
	v_pk_add_f32 v[204:205], v[212:213], 1.0 op_sel_hi:[1,0]
	v_pk_add_f32 v[206:207], v[206:207], 1.0 op_sel_hi:[1,0]
	v_mul_f32_e32 v212, v205, v204
	v_mul_f32_e32 v213, v207, v206
	s_nop 0
	v_mul_f32_e32 v203, v212, v213
	v_rcp_f32_e32 v203, v203
	s_nop 0
	v_mul_f32_e32 v216, v213, v203
	v_mul_f32_e32 v212, v212, v203
	v_pk_mul_f32 v[204:205], v[204:205], v[216:217] op_sel_hi:[1,0]
	v_pk_mul_f32 v[206:207], v[206:207], v[212:213] op_sel_hi:[1,0]
	v_pk_mul_f32 v[216:217], v[116:117], v[206:207]
	v_pk_mul_f32 v[206:207], v[114:115], v[204:205]
	v_cvt_pk_bf16_f32 v204, v176, v177
	v_lshl_add_u64 v[176:177], v[172:173], 1, s[86:87]
	v_cvt_pk_bf16_f32 v205, v210, v211
	v_cvt_pk_bf16_f32 v206, v206, v207
	v_cvt_pk_bf16_f32 v207, v216, v217
	v_lshl_add_u64 v[208:209], v[176:177], 0, v[208:209]
	global_store_dwordx4 v[208:209], v[204:207], off
	v_or_b32_e32 v203, 16, v202
	v_mad_u64_u32 v[208:209], s[10:11], s56, v203, 0
	v_pk_mul_f32 v[206:207], v[110:111], s[8:9] op_sel_hi:[1,0]
	v_mul_lo_u32 v204, s57, v203
	v_min_f32_e32 v203, 0x41e6d4ca, v206
	v_add3_u32 v209, v209, v0, v204
	v_pk_mul_f32 v[204:205], v[112:113], s[8:9] op_sel_hi:[1,0]
	v_exp_f32_e32 v211, v203
	v_min_f32_e32 v203, 0x41e6d4ca, v207
	v_exp_f32_e32 v210, v203
	v_min_f32_e32 v203, 0x41e6d4ca, v204
	v_exp_f32_e32 v207, v203
	v_min_f32_e32 v203, 0x41e6d4ca, v205
	v_exp_f32_e32 v206, v203
	v_pk_add_f32 v[204:205], v[210:211], 1.0 op_sel_hi:[1,0]
	v_lshlrev_b64 v[208:209], 1, v[208:209]
	v_pk_add_f32 v[206:207], v[206:207], 1.0 op_sel_hi:[1,0]
	v_mul_f32_e32 v210, v205, v204
	v_mul_f32_e32 v211, v207, v206
	s_nop 0
	v_mul_f32_e32 v203, v210, v211
	v_rcp_f32_e32 v203, v203
	s_nop 0
	v_mul_f32_e32 v212, v211, v203
	v_mul_f32_e32 v210, v210, v203
	v_pk_mul_f32 v[204:205], v[204:205], v[212:213] op_sel_hi:[1,0]
	v_pk_mul_f32 v[206:207], v[206:207], v[210:211] op_sel_hi:[1,0]
	v_pk_mul_f32 v[206:207], v[112:113], v[206:207]
	v_pk_mul_f32 v[212:213], v[106:107], s[8:9] op_sel_hi:[1,0]
	s_nop 0
	v_min_f32_e32 v203, 0x41e6d4ca, v212
	v_pk_mul_f32 v[204:205], v[110:111], v[204:205]
	v_pk_mul_f32 v[210:211], v[108:109], s[8:9] op_sel_hi:[1,0]
	v_exp_f32_e32 v217, v203
	v_min_f32_e32 v203, 0x41e6d4ca, v213
	v_exp_f32_e32 v216, v203
	v_min_f32_e32 v203, 0x41e6d4ca, v210
	v_exp_f32_e32 v213, v203
	v_min_f32_e32 v203, 0x41e6d4ca, v211
	v_exp_f32_e32 v212, v203
	v_pk_add_f32 v[210:211], v[216:217], 1.0 op_sel_hi:[1,0]
	v_cvt_pk_bf16_f32 v204, v204, v205
	v_pk_add_f32 v[212:213], v[212:213], 1.0 op_sel_hi:[1,0]
	v_mul_f32_e32 v216, v211, v210
	v_mul_f32_e32 v217, v213, v212
	v_cvt_pk_bf16_f32 v205, v206, v207
	v_mul_f32_e32 v203, v216, v217
	v_rcp_f32_e32 v203, v203
	s_nop 0
	v_mul_f32_e32 v218, v217, v203
	v_mul_f32_e32 v216, v216, v203
	v_pk_mul_f32 v[210:211], v[210:211], v[218:219] op_sel_hi:[1,0]
	v_pk_mul_f32 v[212:213], v[212:213], v[216:217] op_sel_hi:[1,0]
	v_pk_mul_f32 v[212:213], v[108:109], v[212:213]
	v_pk_mul_f32 v[210:211], v[106:107], v[210:211]
	v_cvt_pk_bf16_f32 v207, v212, v213
	v_cvt_pk_bf16_f32 v206, v210, v211
	v_lshl_add_u64 v[210:211], v[174:175], 0, v[208:209]
	global_store_dwordx4 v[210:211], v[204:207], off
	v_lshl_add_u64 v[208:209], v[176:177], 0, v[208:209]
	s_nop 0
	v_pk_mul_f32 v[206:207], v[102:103], s[8:9] op_sel_hi:[1,0]
	v_pk_mul_f32 v[204:205], v[104:105], s[8:9] op_sel_hi:[1,0]
	v_min_f32_e32 v203, 0x41e6d4ca, v206
	v_exp_f32_e32 v211, v203
	v_min_f32_e32 v203, 0x41e6d4ca, v207
	v_exp_f32_e32 v210, v203
	v_min_f32_e32 v203, 0x41e6d4ca, v204
	v_exp_f32_e32 v207, v203
	v_min_f32_e32 v203, 0x41e6d4ca, v205
	v_exp_f32_e32 v206, v203
	v_pk_add_f32 v[204:205], v[210:211], 1.0 op_sel_hi:[1,0]
	v_pk_add_f32 v[206:207], v[206:207], 1.0 op_sel_hi:[1,0]
	v_mul_f32_e32 v210, v205, v204
	v_mul_f32_e32 v211, v207, v206
	s_nop 0
	v_mul_f32_e32 v203, v210, v211
	v_rcp_f32_e32 v203, v203
	s_nop 0
	v_mul_f32_e32 v212, v211, v203
	v_mul_f32_e32 v210, v210, v203
	v_pk_mul_f32 v[204:205], v[204:205], v[212:213] op_sel_hi:[1,0]
	v_pk_mul_f32 v[206:207], v[206:207], v[210:211] op_sel_hi:[1,0]
	v_pk_mul_f32 v[206:207], v[104:105], v[206:207]
	v_pk_mul_f32 v[212:213], v[98:99], s[8:9] op_sel_hi:[1,0]
	s_nop 0
	v_min_f32_e32 v203, 0x41e6d4ca, v212
	v_pk_mul_f32 v[204:205], v[102:103], v[204:205]
	v_pk_mul_f32 v[210:211], v[100:101], s[8:9] op_sel_hi:[1,0]
	v_exp_f32_e32 v217, v203
	v_min_f32_e32 v203, 0x41e6d4ca, v213
	v_exp_f32_e32 v216, v203
	v_min_f32_e32 v203, 0x41e6d4ca, v210
	v_exp_f32_e32 v213, v203
	v_min_f32_e32 v203, 0x41e6d4ca, v211
	v_exp_f32_e32 v212, v203
	v_pk_add_f32 v[210:211], v[216:217], 1.0 op_sel_hi:[1,0]
	v_cvt_pk_bf16_f32 v204, v204, v205
	v_pk_add_f32 v[212:213], v[212:213], 1.0 op_sel_hi:[1,0]
	v_mul_f32_e32 v216, v211, v210
	v_mul_f32_e32 v217, v213, v212
	v_cvt_pk_bf16_f32 v205, v206, v207
	v_mul_f32_e32 v203, v216, v217
	v_rcp_f32_e32 v203, v203
	s_nop 0
	v_mul_f32_e32 v218, v217, v203
	v_mul_f32_e32 v216, v216, v203
	v_pk_mul_f32 v[210:211], v[210:211], v[218:219] op_sel_hi:[1,0]
	v_pk_mul_f32 v[212:213], v[212:213], v[216:217] op_sel_hi:[1,0]
	v_pk_mul_f32 v[212:213], v[100:101], v[212:213]
	v_pk_mul_f32 v[210:211], v[98:99], v[210:211]
	v_cvt_pk_bf16_f32 v207, v212, v213
	v_cvt_pk_bf16_f32 v206, v210, v211
	global_store_dwordx4 v[208:209], v[204:207], off
	v_or_b32_e32 v203, 32, v202
	v_mad_u64_u32 v[208:209], s[10:11], s56, v203, 0
	v_pk_mul_f32 v[206:207], v[94:95], s[8:9] op_sel_hi:[1,0]
	v_mul_lo_u32 v204, s57, v203
	v_min_f32_e32 v203, 0x41e6d4ca, v206
	v_add3_u32 v209, v209, v0, v204
	v_pk_mul_f32 v[204:205], v[96:97], s[8:9] op_sel_hi:[1,0]
	v_exp_f32_e32 v211, v203
	v_min_f32_e32 v203, 0x41e6d4ca, v207
	v_exp_f32_e32 v210, v203
	v_min_f32_e32 v203, 0x41e6d4ca, v204
	v_exp_f32_e32 v207, v203
	v_min_f32_e32 v203, 0x41e6d4ca, v205
	v_exp_f32_e32 v206, v203
	v_pk_add_f32 v[204:205], v[210:211], 1.0 op_sel_hi:[1,0]
	v_lshlrev_b64 v[208:209], 1, v[208:209]
	v_pk_add_f32 v[206:207], v[206:207], 1.0 op_sel_hi:[1,0]
	v_mul_f32_e32 v210, v205, v204
	v_mul_f32_e32 v211, v207, v206
	s_nop 0
	v_mul_f32_e32 v203, v210, v211
	v_rcp_f32_e32 v203, v203
	s_nop 0
	v_mul_f32_e32 v212, v211, v203
	v_mul_f32_e32 v210, v210, v203
	v_pk_mul_f32 v[204:205], v[204:205], v[212:213] op_sel_hi:[1,0]
	v_pk_mul_f32 v[206:207], v[206:207], v[210:211] op_sel_hi:[1,0]
	v_pk_mul_f32 v[206:207], v[96:97], v[206:207]
	v_pk_mul_f32 v[212:213], v[90:91], s[8:9] op_sel_hi:[1,0]
	s_nop 0
	v_min_f32_e32 v203, 0x41e6d4ca, v212
	v_pk_mul_f32 v[204:205], v[94:95], v[204:205]
	v_pk_mul_f32 v[210:211], v[92:93], s[8:9] op_sel_hi:[1,0]
	v_exp_f32_e32 v217, v203
	v_min_f32_e32 v203, 0x41e6d4ca, v213
	v_exp_f32_e32 v216, v203
	v_min_f32_e32 v203, 0x41e6d4ca, v210
	v_exp_f32_e32 v213, v203
	v_min_f32_e32 v203, 0x41e6d4ca, v211
	v_exp_f32_e32 v212, v203
	v_pk_add_f32 v[210:211], v[216:217], 1.0 op_sel_hi:[1,0]
	v_cvt_pk_bf16_f32 v204, v204, v205
	v_pk_add_f32 v[212:213], v[212:213], 1.0 op_sel_hi:[1,0]
	v_mul_f32_e32 v216, v211, v210
	v_mul_f32_e32 v217, v213, v212
	v_cvt_pk_bf16_f32 v205, v206, v207
	v_mul_f32_e32 v203, v216, v217
	v_rcp_f32_e32 v203, v203
	s_nop 0
	v_mul_f32_e32 v218, v217, v203
	v_mul_f32_e32 v216, v216, v203
	v_pk_mul_f32 v[210:211], v[210:211], v[218:219] op_sel_hi:[1,0]
	v_pk_mul_f32 v[212:213], v[212:213], v[216:217] op_sel_hi:[1,0]
	v_pk_mul_f32 v[212:213], v[92:93], v[212:213]
	v_pk_mul_f32 v[210:211], v[90:91], v[210:211]
	v_cvt_pk_bf16_f32 v207, v212, v213
	v_cvt_pk_bf16_f32 v206, v210, v211
	v_lshl_add_u64 v[210:211], v[174:175], 0, v[208:209]
	global_store_dwordx4 v[210:211], v[204:207], off
	v_lshl_add_u64 v[208:209], v[176:177], 0, v[208:209]
	s_nop 0
	v_pk_mul_f32 v[206:207], v[86:87], s[8:9] op_sel_hi:[1,0]
	v_pk_mul_f32 v[204:205], v[88:89], s[8:9] op_sel_hi:[1,0]
	v_min_f32_e32 v203, 0x41e6d4ca, v206
	v_exp_f32_e32 v211, v203
	v_min_f32_e32 v203, 0x41e6d4ca, v207
	v_exp_f32_e32 v210, v203
	v_min_f32_e32 v203, 0x41e6d4ca, v204
	v_exp_f32_e32 v207, v203
	v_min_f32_e32 v203, 0x41e6d4ca, v205
	v_exp_f32_e32 v206, v203
	v_pk_add_f32 v[204:205], v[210:211], 1.0 op_sel_hi:[1,0]
	v_pk_add_f32 v[206:207], v[206:207], 1.0 op_sel_hi:[1,0]
	v_mul_f32_e32 v210, v205, v204
	v_mul_f32_e32 v211, v207, v206
	s_nop 0
	v_mul_f32_e32 v203, v210, v211
	v_rcp_f32_e32 v203, v203
	s_nop 0
	v_mul_f32_e32 v212, v211, v203
	v_mul_f32_e32 v210, v210, v203
	v_pk_mul_f32 v[204:205], v[204:205], v[212:213] op_sel_hi:[1,0]
	v_pk_mul_f32 v[206:207], v[206:207], v[210:211] op_sel_hi:[1,0]
	v_pk_mul_f32 v[206:207], v[88:89], v[206:207]
	v_pk_mul_f32 v[212:213], v[82:83], s[8:9] op_sel_hi:[1,0]
	s_nop 0
	v_min_f32_e32 v203, 0x41e6d4ca, v212
	v_pk_mul_f32 v[204:205], v[86:87], v[204:205]
	v_pk_mul_f32 v[210:211], v[84:85], s[8:9] op_sel_hi:[1,0]
	v_exp_f32_e32 v217, v203
	v_min_f32_e32 v203, 0x41e6d4ca, v213
	v_exp_f32_e32 v216, v203
	v_min_f32_e32 v203, 0x41e6d4ca, v210
	v_exp_f32_e32 v213, v203
	v_min_f32_e32 v203, 0x41e6d4ca, v211
	v_exp_f32_e32 v212, v203
	v_pk_add_f32 v[210:211], v[216:217], 1.0 op_sel_hi:[1,0]
	v_cvt_pk_bf16_f32 v204, v204, v205
	v_pk_add_f32 v[212:213], v[212:213], 1.0 op_sel_hi:[1,0]
	v_mul_f32_e32 v216, v211, v210
	v_mul_f32_e32 v217, v213, v212
	v_cvt_pk_bf16_f32 v205, v206, v207
	v_mul_f32_e32 v203, v216, v217
	v_rcp_f32_e32 v203, v203
	s_nop 0
	v_mul_f32_e32 v218, v217, v203
	v_mul_f32_e32 v216, v216, v203
	v_pk_mul_f32 v[210:211], v[210:211], v[218:219] op_sel_hi:[1,0]
	v_pk_mul_f32 v[212:213], v[212:213], v[216:217] op_sel_hi:[1,0]
	v_pk_mul_f32 v[212:213], v[84:85], v[212:213]
	v_pk_mul_f32 v[210:211], v[82:83], v[210:211]
	v_cvt_pk_bf16_f32 v207, v212, v213
	v_cvt_pk_bf16_f32 v206, v210, v211
	v_or_b32_e32 v203, 48, v202
	global_store_dwordx4 v[208:209], v[204:207], off
	v_mad_u64_u32 v[208:209], s[10:11], s56, v203, 0
	s_nop 0
	v_mul_lo_u32 v204, s57, v203
	v_pk_mul_f32 v[206:207], v[78:79], s[8:9] op_sel_hi:[1,0]
	v_add3_u32 v209, v209, v0, v204
	v_min_f32_e32 v0, 0x41e6d4ca, v206
	v_pk_mul_f32 v[204:205], v[80:81], s[8:9] op_sel_hi:[1,0]
	v_exp_f32_e32 v211, v0
	v_min_f32_e32 v0, 0x41e6d4ca, v207
	v_exp_f32_e32 v210, v0
	v_min_f32_e32 v0, 0x41e6d4ca, v204
	v_exp_f32_e32 v207, v0
	v_min_f32_e32 v0, 0x41e6d4ca, v205
	v_exp_f32_e32 v206, v0
	v_pk_add_f32 v[204:205], v[210:211], 1.0 op_sel_hi:[1,0]
	v_lshlrev_b64 v[208:209], 1, v[208:209]
	v_pk_add_f32 v[206:207], v[206:207], 1.0 op_sel_hi:[1,0]
	v_mul_f32_e32 v210, v205, v204
	v_mul_f32_e32 v211, v207, v206
	v_mul_f32_e32 v0, v210, v211
	v_rcp_f32_e32 v203, v0
	s_nop 0
	v_mul_f32_e32 v210, v210, v203
	v_pk_mul_f32 v[206:207], v[206:207], v[210:211] op_sel_hi:[1,0]
	v_mul_f32_e32 v0, v211, v203
	v_pk_mul_f32 v[206:207], v[80:81], v[206:207]
	v_pk_mul_f32 v[212:213], v[74:75], s[8:9] op_sel_hi:[1,0]
	v_pk_mul_f32 v[204:205], v[204:205], v[0:1] op_sel_hi:[1,0]
	v_min_f32_e32 v0, 0x41e6d4ca, v212
	v_pk_mul_f32 v[204:205], v[78:79], v[204:205]
	v_pk_mul_f32 v[210:211], v[76:77], s[8:9] op_sel_hi:[1,0]
	v_exp_f32_e32 v217, v0
	v_min_f32_e32 v0, 0x41e6d4ca, v213
	v_exp_f32_e32 v216, v0
	v_min_f32_e32 v0, 0x41e6d4ca, v210
	v_exp_f32_e32 v213, v0
	v_min_f32_e32 v0, 0x41e6d4ca, v211
	v_exp_f32_e32 v212, v0
	v_pk_add_f32 v[210:211], v[216:217], 1.0 op_sel_hi:[1,0]
	v_cvt_pk_bf16_f32 v204, v204, v205
	v_pk_add_f32 v[212:213], v[212:213], 1.0 op_sel_hi:[1,0]
	v_mul_f32_e32 v216, v211, v210
	v_mul_f32_e32 v217, v213, v212
	v_mul_f32_e32 v0, v216, v217
	v_rcp_f32_e32 v203, v0
	v_cvt_pk_bf16_f32 v205, v206, v207
	v_mul_f32_e32 v0, v217, v203
	v_mul_f32_e32 v216, v216, v203
	v_pk_mul_f32 v[210:211], v[210:211], v[0:1] op_sel_hi:[1,0]
	v_pk_mul_f32 v[212:213], v[212:213], v[216:217] op_sel_hi:[1,0]
	v_pk_mul_f32 v[212:213], v[76:77], v[212:213]
	v_pk_mul_f32 v[210:211], v[74:75], v[210:211]
	v_cvt_pk_bf16_f32 v207, v212, v213
	v_cvt_pk_bf16_f32 v206, v210, v211
	v_lshl_add_u64 v[210:211], v[174:175], 0, v[208:209]
	global_store_dwordx4 v[210:211], v[204:207], off
	v_lshl_add_u64 v[208:209], v[176:177], 0, v[208:209]
	s_nop 0
	v_pk_mul_f32 v[206:207], v[70:71], s[8:9] op_sel_hi:[1,0]
	v_pk_mul_f32 v[204:205], v[72:73], s[8:9] op_sel_hi:[1,0]
	v_min_f32_e32 v0, 0x41e6d4ca, v206
	v_exp_f32_e32 v211, v0
	v_min_f32_e32 v0, 0x41e6d4ca, v207
	v_exp_f32_e32 v210, v0
	v_min_f32_e32 v0, 0x41e6d4ca, v204
	v_exp_f32_e32 v207, v0
	v_min_f32_e32 v0, 0x41e6d4ca, v205
	v_exp_f32_e32 v206, v0
	v_pk_add_f32 v[204:205], v[210:211], 1.0 op_sel_hi:[1,0]
	v_pk_add_f32 v[206:207], v[206:207], 1.0 op_sel_hi:[1,0]
	v_mul_f32_e32 v210, v205, v204
	v_mul_f32_e32 v211, v207, v206
	v_mul_f32_e32 v0, v210, v211
	v_rcp_f32_e32 v203, v0
	s_nop 0
	v_mul_f32_e32 v210, v210, v203
	v_pk_mul_f32 v[206:207], v[206:207], v[210:211] op_sel_hi:[1,0]
	v_mul_f32_e32 v0, v211, v203
	v_pk_mul_f32 v[206:207], v[72:73], v[206:207]
	v_pk_mul_f32 v[212:213], v[66:67], s[8:9] op_sel_hi:[1,0]
	v_pk_mul_f32 v[204:205], v[204:205], v[0:1] op_sel_hi:[1,0]
	v_min_f32_e32 v0, 0x41e6d4ca, v212
	v_pk_mul_f32 v[204:205], v[70:71], v[204:205]
	v_pk_mul_f32 v[210:211], v[68:69], s[8:9] op_sel_hi:[1,0]
	v_exp_f32_e32 v217, v0
	v_min_f32_e32 v0, 0x41e6d4ca, v213
	v_exp_f32_e32 v216, v0
	v_min_f32_e32 v0, 0x41e6d4ca, v210
	v_exp_f32_e32 v213, v0
	v_min_f32_e32 v0, 0x41e6d4ca, v211
	v_exp_f32_e32 v212, v0
	v_pk_add_f32 v[210:211], v[216:217], 1.0 op_sel_hi:[1,0]
	v_cvt_pk_bf16_f32 v204, v204, v205
	v_pk_add_f32 v[212:213], v[212:213], 1.0 op_sel_hi:[1,0]
	v_mul_f32_e32 v216, v211, v210
	v_mul_f32_e32 v217, v213, v212
	v_mul_f32_e32 v0, v216, v217
	v_rcp_f32_e32 v203, v0
	v_cvt_pk_bf16_f32 v205, v206, v207
	v_mul_f32_e32 v0, v217, v203
	v_mul_f32_e32 v216, v216, v203
	v_pk_mul_f32 v[210:211], v[210:211], v[0:1] op_sel_hi:[1,0]
	v_pk_mul_f32 v[212:213], v[212:213], v[216:217] op_sel_hi:[1,0]
	v_pk_mul_f32 v[212:213], v[68:69], v[212:213]
	v_pk_mul_f32 v[210:211], v[66:67], v[210:211]
	v_cvt_pk_bf16_f32 v207, v212, v213
	v_cvt_pk_bf16_f32 v206, v210, v211
	v_add_u32_e32 v0, 0x80, v202
	global_store_dwordx4 v[208:209], v[204:207], off
	v_ashrrev_i32_e32 v203, 31, v0
	v_mul_lo_u32 v203, s56, v203
	v_pk_mul_f32 v[206:207], v[62:63], s[8:9] op_sel_hi:[1,0]
	v_mul_lo_u32 v204, s57, v0
	v_mad_u64_u32 v[208:209], s[10:11], s56, v0, 0
	v_min_f32_e32 v0, 0x41e6d4ca, v206
	v_add3_u32 v209, v209, v203, v204
	v_pk_mul_f32 v[204:205], v[64:65], s[8:9] op_sel_hi:[1,0]
	v_exp_f32_e32 v211, v0
	v_min_f32_e32 v0, 0x41e6d4ca, v207
	v_exp_f32_e32 v210, v0
	v_min_f32_e32 v0, 0x41e6d4ca, v204
	v_exp_f32_e32 v207, v0
	v_min_f32_e32 v0, 0x41e6d4ca, v205
	v_exp_f32_e32 v206, v0
	v_pk_add_f32 v[204:205], v[210:211], 1.0 op_sel_hi:[1,0]
	v_lshlrev_b64 v[208:209], 1, v[208:209]
	v_pk_add_f32 v[206:207], v[206:207], 1.0 op_sel_hi:[1,0]
	v_mul_f32_e32 v210, v205, v204
	v_mul_f32_e32 v211, v207, v206
	v_mul_f32_e32 v0, v210, v211
	v_rcp_f32_e32 v203, v0
	s_nop 0
	v_mul_f32_e32 v210, v210, v203
	v_pk_mul_f32 v[206:207], v[206:207], v[210:211] op_sel_hi:[1,0]
	v_mul_f32_e32 v0, v211, v203
	v_pk_mul_f32 v[206:207], v[64:65], v[206:207]
	v_pk_mul_f32 v[212:213], v[58:59], s[8:9] op_sel_hi:[1,0]
	v_pk_mul_f32 v[204:205], v[204:205], v[0:1] op_sel_hi:[1,0]
	v_min_f32_e32 v0, 0x41e6d4ca, v212
	v_pk_mul_f32 v[204:205], v[62:63], v[204:205]
	v_pk_mul_f32 v[210:211], v[60:61], s[8:9] op_sel_hi:[1,0]
	v_exp_f32_e32 v217, v0
	v_min_f32_e32 v0, 0x41e6d4ca, v213
	v_exp_f32_e32 v216, v0
	v_min_f32_e32 v0, 0x41e6d4ca, v210
	v_exp_f32_e32 v213, v0
	v_min_f32_e32 v0, 0x41e6d4ca, v211
	v_exp_f32_e32 v212, v0
	v_pk_add_f32 v[210:211], v[216:217], 1.0 op_sel_hi:[1,0]
	v_cvt_pk_bf16_f32 v204, v204, v205
	v_pk_add_f32 v[212:213], v[212:213], 1.0 op_sel_hi:[1,0]
	v_mul_f32_e32 v216, v211, v210
	v_mul_f32_e32 v217, v213, v212
	v_mul_f32_e32 v0, v216, v217
	v_rcp_f32_e32 v203, v0
	v_cvt_pk_bf16_f32 v205, v206, v207
	v_mul_f32_e32 v0, v217, v203
	v_mul_f32_e32 v216, v216, v203
	v_pk_mul_f32 v[210:211], v[210:211], v[0:1] op_sel_hi:[1,0]
	v_pk_mul_f32 v[212:213], v[212:213], v[216:217] op_sel_hi:[1,0]
	v_pk_mul_f32 v[212:213], v[60:61], v[212:213]
	v_pk_mul_f32 v[210:211], v[58:59], v[210:211]
	v_cvt_pk_bf16_f32 v207, v212, v213
	v_cvt_pk_bf16_f32 v206, v210, v211
	v_lshl_add_u64 v[210:211], v[174:175], 0, v[208:209]
	global_store_dwordx4 v[210:211], v[204:207], off
	v_lshl_add_u64 v[208:209], v[176:177], 0, v[208:209]
	s_nop 0
	v_pk_mul_f32 v[206:207], v[54:55], s[8:9] op_sel_hi:[1,0]
	v_pk_mul_f32 v[204:205], v[56:57], s[8:9] op_sel_hi:[1,0]
	v_min_f32_e32 v0, 0x41e6d4ca, v206
	v_exp_f32_e32 v211, v0
	v_min_f32_e32 v0, 0x41e6d4ca, v207
	v_exp_f32_e32 v210, v0
	v_min_f32_e32 v0, 0x41e6d4ca, v204
	v_exp_f32_e32 v207, v0
	v_min_f32_e32 v0, 0x41e6d4ca, v205
	v_exp_f32_e32 v206, v0
	v_pk_add_f32 v[204:205], v[210:211], 1.0 op_sel_hi:[1,0]
	v_pk_add_f32 v[206:207], v[206:207], 1.0 op_sel_hi:[1,0]
	v_mul_f32_e32 v210, v205, v204
	v_mul_f32_e32 v211, v207, v206
	v_mul_f32_e32 v0, v210, v211
	v_rcp_f32_e32 v203, v0
	s_nop 0
	v_mul_f32_e32 v210, v210, v203
	v_pk_mul_f32 v[206:207], v[206:207], v[210:211] op_sel_hi:[1,0]
	v_mul_f32_e32 v0, v211, v203
	v_pk_mul_f32 v[206:207], v[56:57], v[206:207]
	v_pk_mul_f32 v[212:213], v[50:51], s[8:9] op_sel_hi:[1,0]
	v_pk_mul_f32 v[204:205], v[204:205], v[0:1] op_sel_hi:[1,0]
	v_min_f32_e32 v0, 0x41e6d4ca, v212
	v_pk_mul_f32 v[204:205], v[54:55], v[204:205]
	v_pk_mul_f32 v[210:211], v[52:53], s[8:9] op_sel_hi:[1,0]
	v_exp_f32_e32 v217, v0
	v_min_f32_e32 v0, 0x41e6d4ca, v213
	v_exp_f32_e32 v216, v0
	v_min_f32_e32 v0, 0x41e6d4ca, v210
	v_exp_f32_e32 v213, v0
	v_min_f32_e32 v0, 0x41e6d4ca, v211
	v_exp_f32_e32 v212, v0
	v_pk_add_f32 v[210:211], v[216:217], 1.0 op_sel_hi:[1,0]
	v_cvt_pk_bf16_f32 v204, v204, v205
	v_pk_add_f32 v[212:213], v[212:213], 1.0 op_sel_hi:[1,0]
	v_mul_f32_e32 v216, v211, v210
	v_mul_f32_e32 v217, v213, v212
	v_mul_f32_e32 v0, v216, v217
	v_rcp_f32_e32 v203, v0
	v_cvt_pk_bf16_f32 v205, v206, v207
	v_mul_f32_e32 v0, v217, v203
	v_mul_f32_e32 v216, v216, v203
	v_pk_mul_f32 v[210:211], v[210:211], v[0:1] op_sel_hi:[1,0]
	v_pk_mul_f32 v[212:213], v[212:213], v[216:217] op_sel_hi:[1,0]
	v_pk_mul_f32 v[212:213], v[52:53], v[212:213]
	v_pk_mul_f32 v[210:211], v[50:51], v[210:211]
	v_cvt_pk_bf16_f32 v207, v212, v213
	v_cvt_pk_bf16_f32 v206, v210, v211
	v_add_u32_e32 v0, 0x90, v202
	global_store_dwordx4 v[208:209], v[204:207], off
	v_ashrrev_i32_e32 v203, 31, v0
	v_mul_lo_u32 v203, s56, v203
	v_pk_mul_f32 v[206:207], v[46:47], s[8:9] op_sel_hi:[1,0]
	v_mul_lo_u32 v204, s57, v0
	v_mad_u64_u32 v[208:209], s[10:11], s56, v0, 0
	v_min_f32_e32 v0, 0x41e6d4ca, v206
	v_add3_u32 v209, v209, v203, v204
	v_pk_mul_f32 v[204:205], v[48:49], s[8:9] op_sel_hi:[1,0]
	v_exp_f32_e32 v211, v0
	v_min_f32_e32 v0, 0x41e6d4ca, v207
	v_exp_f32_e32 v210, v0
	v_min_f32_e32 v0, 0x41e6d4ca, v204
	v_exp_f32_e32 v207, v0
	v_min_f32_e32 v0, 0x41e6d4ca, v205
	v_exp_f32_e32 v206, v0
	v_pk_add_f32 v[204:205], v[210:211], 1.0 op_sel_hi:[1,0]
	v_lshlrev_b64 v[208:209], 1, v[208:209]
	v_pk_add_f32 v[206:207], v[206:207], 1.0 op_sel_hi:[1,0]
	v_mul_f32_e32 v210, v205, v204
	v_mul_f32_e32 v211, v207, v206
	v_mul_f32_e32 v0, v210, v211
	v_rcp_f32_e32 v203, v0
	s_nop 0
	v_mul_f32_e32 v210, v210, v203
	v_pk_mul_f32 v[206:207], v[206:207], v[210:211] op_sel_hi:[1,0]
	v_mul_f32_e32 v0, v211, v203
	v_pk_mul_f32 v[206:207], v[48:49], v[206:207]
	v_pk_mul_f32 v[212:213], v[42:43], s[8:9] op_sel_hi:[1,0]
	v_pk_mul_f32 v[204:205], v[204:205], v[0:1] op_sel_hi:[1,0]
	v_min_f32_e32 v0, 0x41e6d4ca, v212
	v_pk_mul_f32 v[204:205], v[46:47], v[204:205]
	v_pk_mul_f32 v[210:211], v[44:45], s[8:9] op_sel_hi:[1,0]
	v_exp_f32_e32 v217, v0
	v_min_f32_e32 v0, 0x41e6d4ca, v213
	v_exp_f32_e32 v216, v0
	v_min_f32_e32 v0, 0x41e6d4ca, v210
	v_exp_f32_e32 v213, v0
	v_min_f32_e32 v0, 0x41e6d4ca, v211
	v_exp_f32_e32 v212, v0
	v_pk_add_f32 v[210:211], v[216:217], 1.0 op_sel_hi:[1,0]
	v_cvt_pk_bf16_f32 v204, v204, v205
	v_pk_add_f32 v[212:213], v[212:213], 1.0 op_sel_hi:[1,0]
	v_mul_f32_e32 v216, v211, v210
	v_mul_f32_e32 v217, v213, v212
	v_mul_f32_e32 v0, v216, v217
	v_rcp_f32_e32 v203, v0
	v_cvt_pk_bf16_f32 v205, v206, v207
	v_mul_f32_e32 v0, v217, v203
	v_mul_f32_e32 v216, v216, v203
	v_pk_mul_f32 v[210:211], v[210:211], v[0:1] op_sel_hi:[1,0]
	v_pk_mul_f32 v[212:213], v[212:213], v[216:217] op_sel_hi:[1,0]
	v_pk_mul_f32 v[212:213], v[44:45], v[212:213]
	v_pk_mul_f32 v[210:211], v[42:43], v[210:211]
	v_cvt_pk_bf16_f32 v207, v212, v213
	v_cvt_pk_bf16_f32 v206, v210, v211
	v_lshl_add_u64 v[210:211], v[174:175], 0, v[208:209]
	global_store_dwordx4 v[210:211], v[204:207], off
	v_lshl_add_u64 v[208:209], v[176:177], 0, v[208:209]
	s_nop 0
	v_pk_mul_f32 v[206:207], v[38:39], s[8:9] op_sel_hi:[1,0]
	v_pk_mul_f32 v[204:205], v[40:41], s[8:9] op_sel_hi:[1,0]
	v_min_f32_e32 v0, 0x41e6d4ca, v206
	v_exp_f32_e32 v211, v0
	v_min_f32_e32 v0, 0x41e6d4ca, v207
	v_exp_f32_e32 v210, v0
	v_min_f32_e32 v0, 0x41e6d4ca, v204
	v_exp_f32_e32 v207, v0
	v_min_f32_e32 v0, 0x41e6d4ca, v205
	v_exp_f32_e32 v206, v0
	v_pk_add_f32 v[204:205], v[210:211], 1.0 op_sel_hi:[1,0]
	v_pk_add_f32 v[206:207], v[206:207], 1.0 op_sel_hi:[1,0]
	v_mul_f32_e32 v210, v205, v204
	v_mul_f32_e32 v211, v207, v206
	v_mul_f32_e32 v0, v210, v211
	v_rcp_f32_e32 v203, v0
	s_nop 0
	v_mul_f32_e32 v210, v210, v203
	v_pk_mul_f32 v[206:207], v[206:207], v[210:211] op_sel_hi:[1,0]
	v_mul_f32_e32 v0, v211, v203
	v_pk_mul_f32 v[206:207], v[40:41], v[206:207]
	v_pk_mul_f32 v[212:213], v[34:35], s[8:9] op_sel_hi:[1,0]
	v_pk_mul_f32 v[204:205], v[204:205], v[0:1] op_sel_hi:[1,0]
	v_min_f32_e32 v0, 0x41e6d4ca, v212
	v_pk_mul_f32 v[204:205], v[38:39], v[204:205]
	v_pk_mul_f32 v[210:211], v[36:37], s[8:9] op_sel_hi:[1,0]
	v_exp_f32_e32 v217, v0
	v_min_f32_e32 v0, 0x41e6d4ca, v213
	v_exp_f32_e32 v216, v0
	v_min_f32_e32 v0, 0x41e6d4ca, v210
	v_exp_f32_e32 v213, v0
	v_min_f32_e32 v0, 0x41e6d4ca, v211
	v_exp_f32_e32 v212, v0
	v_pk_add_f32 v[210:211], v[216:217], 1.0 op_sel_hi:[1,0]
	v_cvt_pk_bf16_f32 v204, v204, v205
	v_pk_add_f32 v[212:213], v[212:213], 1.0 op_sel_hi:[1,0]
	v_mul_f32_e32 v216, v211, v210
	v_mul_f32_e32 v217, v213, v212
	v_mul_f32_e32 v0, v216, v217
	v_rcp_f32_e32 v203, v0
	v_cvt_pk_bf16_f32 v205, v206, v207
	v_mul_f32_e32 v0, v217, v203
	v_mul_f32_e32 v216, v216, v203
	v_pk_mul_f32 v[210:211], v[210:211], v[0:1] op_sel_hi:[1,0]
	v_pk_mul_f32 v[212:213], v[212:213], v[216:217] op_sel_hi:[1,0]
	v_pk_mul_f32 v[212:213], v[36:37], v[212:213]
	v_pk_mul_f32 v[210:211], v[34:35], v[210:211]
	v_cvt_pk_bf16_f32 v207, v212, v213
	v_cvt_pk_bf16_f32 v206, v210, v211
	v_add_u32_e32 v0, 0xa0, v202
	global_store_dwordx4 v[208:209], v[204:207], off
	v_ashrrev_i32_e32 v203, 31, v0
	v_mul_lo_u32 v203, s56, v203
	v_pk_mul_f32 v[206:207], v[30:31], s[8:9] op_sel_hi:[1,0]
	v_mul_lo_u32 v204, s57, v0
	v_mad_u64_u32 v[208:209], s[10:11], s56, v0, 0
	v_min_f32_e32 v0, 0x41e6d4ca, v206
	v_add3_u32 v209, v209, v203, v204
	v_pk_mul_f32 v[204:205], v[32:33], s[8:9] op_sel_hi:[1,0]
	v_exp_f32_e32 v211, v0
	v_min_f32_e32 v0, 0x41e6d4ca, v207
	v_exp_f32_e32 v210, v0
	v_min_f32_e32 v0, 0x41e6d4ca, v204
	v_exp_f32_e32 v207, v0
	v_min_f32_e32 v0, 0x41e6d4ca, v205
	v_exp_f32_e32 v206, v0
	v_pk_add_f32 v[204:205], v[210:211], 1.0 op_sel_hi:[1,0]
	v_lshlrev_b64 v[208:209], 1, v[208:209]
	v_pk_add_f32 v[206:207], v[206:207], 1.0 op_sel_hi:[1,0]
	v_mul_f32_e32 v210, v205, v204
	v_mul_f32_e32 v211, v207, v206
	v_mul_f32_e32 v0, v210, v211
	v_rcp_f32_e32 v203, v0
	v_lshl_add_u64 v[176:177], v[176:177], 0, v[208:209]
	v_mul_f32_e32 v210, v210, v203
	v_pk_mul_f32 v[206:207], v[206:207], v[210:211] op_sel_hi:[1,0]
	v_mul_f32_e32 v0, v211, v203
	v_pk_mul_f32 v[206:207], v[32:33], v[206:207]
	v_pk_mul_f32 v[212:213], v[26:27], s[8:9] op_sel_hi:[1,0]
	v_pk_mul_f32 v[204:205], v[204:205], v[0:1] op_sel_hi:[1,0]
	v_min_f32_e32 v0, 0x41e6d4ca, v212
	v_pk_mul_f32 v[204:205], v[30:31], v[204:205]
	v_pk_mul_f32 v[210:211], v[28:29], s[8:9] op_sel_hi:[1,0]
	v_exp_f32_e32 v217, v0
	v_min_f32_e32 v0, 0x41e6d4ca, v213
	v_exp_f32_e32 v216, v0
	v_min_f32_e32 v0, 0x41e6d4ca, v210
	v_exp_f32_e32 v213, v0
	v_min_f32_e32 v0, 0x41e6d4ca, v211
	v_exp_f32_e32 v212, v0
	v_pk_add_f32 v[210:211], v[216:217], 1.0 op_sel_hi:[1,0]
	v_cvt_pk_bf16_f32 v204, v204, v205
	v_pk_add_f32 v[212:213], v[212:213], 1.0 op_sel_hi:[1,0]
	v_mul_f32_e32 v216, v211, v210
	v_mul_f32_e32 v217, v213, v212
	v_mul_f32_e32 v0, v216, v217
	v_rcp_f32_e32 v203, v0
	v_cvt_pk_bf16_f32 v205, v206, v207
	v_mul_f32_e32 v0, v217, v203
	v_mul_f32_e32 v216, v216, v203
	v_pk_mul_f32 v[210:211], v[210:211], v[0:1] op_sel_hi:[1,0]
	v_pk_mul_f32 v[212:213], v[212:213], v[216:217] op_sel_hi:[1,0]
	v_pk_mul_f32 v[212:213], v[28:29], v[212:213]
	v_pk_mul_f32 v[210:211], v[26:27], v[210:211]
	v_cvt_pk_bf16_f32 v207, v212, v213
	v_cvt_pk_bf16_f32 v206, v210, v211
	v_lshl_add_u64 v[210:211], v[174:175], 0, v[208:209]
	global_store_dwordx4 v[210:211], v[204:207], off
	s_nop 1
	v_pk_mul_f32 v[206:207], v[22:23], s[8:9] op_sel_hi:[1,0]
	v_pk_mul_f32 v[204:205], v[24:25], s[8:9] op_sel_hi:[1,0]
	v_min_f32_e32 v0, 0x41e6d4ca, v206
	v_exp_f32_e32 v211, v0
	v_min_f32_e32 v0, 0x41e6d4ca, v207
	v_exp_f32_e32 v210, v0
	v_min_f32_e32 v0, 0x41e6d4ca, v204
	v_exp_f32_e32 v207, v0
	v_min_f32_e32 v0, 0x41e6d4ca, v205
	v_exp_f32_e32 v206, v0
	v_pk_add_f32 v[204:205], v[210:211], 1.0 op_sel_hi:[1,0]
	v_pk_add_f32 v[206:207], v[206:207], 1.0 op_sel_hi:[1,0]
	v_mul_f32_e32 v210, v205, v204
	v_mul_f32_e32 v211, v207, v206
	v_mul_f32_e32 v0, v210, v211
	v_rcp_f32_e32 v203, v0
	s_nop 0
	v_mul_f32_e32 v210, v210, v203
	v_pk_mul_f32 v[206:207], v[206:207], v[210:211] op_sel_hi:[1,0]
	v_mul_f32_e32 v0, v211, v203
	v_pk_mul_f32 v[206:207], v[24:25], v[206:207]
	v_pk_mul_f32 v[212:213], v[18:19], s[8:9] op_sel_hi:[1,0]
	v_pk_mul_f32 v[204:205], v[204:205], v[0:1] op_sel_hi:[1,0]
	v_min_f32_e32 v0, 0x41e6d4ca, v212
	v_pk_mul_f32 v[204:205], v[22:23], v[204:205]
	v_pk_mul_f32 v[210:211], v[20:21], s[8:9] op_sel_hi:[1,0]
	v_exp_f32_e32 v217, v0
	v_min_f32_e32 v0, 0x41e6d4ca, v213
	v_exp_f32_e32 v216, v0
	v_min_f32_e32 v0, 0x41e6d4ca, v210
	v_exp_f32_e32 v213, v0
	v_min_f32_e32 v0, 0x41e6d4ca, v211
	v_exp_f32_e32 v212, v0
	v_pk_add_f32 v[210:211], v[216:217], 1.0 op_sel_hi:[1,0]
	v_cvt_pk_bf16_f32 v204, v204, v205
	v_pk_add_f32 v[212:213], v[212:213], 1.0 op_sel_hi:[1,0]
	v_mul_f32_e32 v216, v211, v210
	v_mul_f32_e32 v217, v213, v212
	v_mul_f32_e32 v0, v216, v217
	v_rcp_f32_e32 v203, v0
	v_cvt_pk_bf16_f32 v205, v206, v207
	v_mul_f32_e32 v0, v217, v203
	v_mul_f32_e32 v216, v216, v203
	v_pk_mul_f32 v[210:211], v[210:211], v[0:1] op_sel_hi:[1,0]
	v_pk_mul_f32 v[212:213], v[212:213], v[216:217] op_sel_hi:[1,0]
	v_pk_mul_f32 v[212:213], v[20:21], v[212:213]
	v_pk_mul_f32 v[210:211], v[18:19], v[210:211]
	v_cvt_pk_bf16_f32 v207, v212, v213
	v_cvt_pk_bf16_f32 v206, v210, v211
	v_add_u32_e32 v0, 0xb0, v202
	global_store_dwordx4 v[176:177], v[204:207], off
	v_ashrrev_i32_e32 v176, 31, v0
	v_mul_lo_u32 v203, s56, v176
	v_pk_mul_f32 v[206:207], v[14:15], s[8:9] op_sel_hi:[1,0]
	v_mul_lo_u32 v204, s57, v0
	v_mad_u64_u32 v[176:177], s[10:11], s56, v0, 0
	v_min_f32_e32 v0, 0x41e6d4ca, v206
	v_add3_u32 v177, v177, v203, v204
	v_pk_mul_f32 v[204:205], v[16:17], s[8:9] op_sel_hi:[1,0]
	v_exp_f32_e32 v209, v0
	v_min_f32_e32 v0, 0x41e6d4ca, v207
	v_exp_f32_e32 v208, v0
	v_min_f32_e32 v0, 0x41e6d4ca, v204
	v_exp_f32_e32 v207, v0
	v_min_f32_e32 v0, 0x41e6d4ca, v205
	v_exp_f32_e32 v206, v0
	v_pk_add_f32 v[204:205], v[208:209], 1.0 op_sel_hi:[1,0]
	v_pk_add_f32 v[206:207], v[206:207], 1.0 op_sel_hi:[1,0]
	v_mul_f32_e32 v208, v205, v204
	v_mul_f32_e32 v209, v207, v206
	v_mul_f32_e32 v0, v208, v209
	v_rcp_f32_e32 v203, v0
	s_nop 0
	v_mul_f32_e32 v208, v208, v203
	v_pk_mul_f32 v[206:207], v[206:207], v[208:209] op_sel_hi:[1,0]
	v_mul_f32_e32 v0, v209, v203
	v_pk_mul_f32 v[144:145], v[16:17], v[206:207]
	v_pk_mul_f32 v[206:207], v[10:11], s[8:9] op_sel_hi:[1,0]
	v_pk_mul_f32 v[204:205], v[204:205], v[0:1] op_sel_hi:[1,0]
	v_min_f32_e32 v0, 0x41e6d4ca, v206
	v_pk_mul_f32 v[142:143], v[14:15], v[204:205]
	v_pk_mul_f32 v[204:205], v[12:13], s[8:9] op_sel_hi:[1,0]
	v_exp_f32_e32 v209, v0
	v_min_f32_e32 v0, 0x41e6d4ca, v207
	v_exp_f32_e32 v208, v0
	v_min_f32_e32 v0, 0x41e6d4ca, v204
	v_exp_f32_e32 v207, v0
	v_min_f32_e32 v0, 0x41e6d4ca, v205
	v_exp_f32_e32 v206, v0
	v_pk_add_f32 v[204:205], v[208:209], 1.0 op_sel_hi:[1,0]
	s_nop 0
	v_mov_b32_e32 v208, v205
	v_pk_add_f32 v[206:207], v[206:207], 1.0 op_sel_hi:[1,0]
	v_mov_b32_e32 v210, v204
	v_mov_b32_e32 v209, v207
	v_mov_b32_e32 v211, v206
	v_pk_mul_f32 v[208:209], v[208:209], v[210:211]
	s_nop 0
	v_mul_f32_e32 v0, v208, v209
	v_rcp_f32_e32 v203, v0
	s_mov_b64 s[10:11], 0
	v_mul_f32_e32 v0, v209, v203
	v_mul_f32_e32 v208, v208, v203
	v_pk_mul_f32 v[204:205], v[204:205], v[0:1] op_sel_hi:[1,0]
	v_pk_mul_f32 v[206:207], v[206:207], v[208:209] op_sel_hi:[1,0]
	s_nop 0
	v_pk_mul_f32 v[206:207], v[12:13], v[206:207]
	v_pk_mul_f32 v[140:141], v[10:11], v[204:205]
	v_cvt_pk_bf16_f32 v138, v142, v143
	v_cvt_pk_bf16_f32 v139, v144, v145
	v_cvt_pk_bf16_f32 v140, v140, v141
	v_cvt_pk_bf16_f32 v141, v206, v207
	v_lshl_add_u64 v[142:143], v[176:177], 1, v[174:175]
	global_store_dwordx4 v[142:143], v[138:141], off
	s_nop 1
	v_pk_mul_f32 v[140:141], v[6:7], s[8:9] op_sel_hi:[1,0]
	v_pk_mul_f32 v[138:139], v[8:9], s[8:9] op_sel_hi:[1,0]
	v_min_f32_e32 v0, 0x41e6d4ca, v140
	v_exp_f32_e32 v143, v0
	v_min_f32_e32 v0, 0x41e6d4ca, v141
	v_exp_f32_e32 v142, v0
	v_min_f32_e32 v0, 0x41e6d4ca, v138
	v_exp_f32_e32 v141, v0
	v_min_f32_e32 v0, 0x41e6d4ca, v139
	v_exp_f32_e32 v140, v0
	v_pk_add_f32 v[138:139], v[142:143], 1.0 op_sel_hi:[1,0]
	v_pk_add_f32 v[140:141], v[140:141], 1.0 op_sel_hi:[1,0]
	v_mul_f32_e32 v142, v139, v138
	v_mul_f32_e32 v143, v141, v140
	s_nop 0
	v_mul_f32_e32 v0, v142, v143
	v_rcp_f32_e32 v144, v0
	s_nop 0
	v_mul_f32_e32 v0, v143, v144
	v_pk_mul_f32 v[138:139], v[138:139], v[0:1] op_sel_hi:[1,0]
	v_mul_f32_e32 v142, v142, v144
	v_pk_mul_f32 v[134:135], v[6:7], v[138:139]
	v_pk_mul_f32 v[138:139], v[2:3], s[8:9] op_sel_hi:[1,0]
	v_pk_mul_f32 v[140:141], v[140:141], v[142:143] op_sel_hi:[1,0]
	v_min_f32_e32 v0, 0x41e6d4ca, v138
	v_pk_mul_f32 v[140:141], v[8:9], v[140:141]
	v_pk_mul_f32 v[136:137], v[4:5], s[8:9] op_sel_hi:[1,0]
	v_exp_f32_e32 v143, v0
	v_min_f32_e32 v0, 0x41e6d4ca, v139
	v_exp_f32_e32 v142, v0
	v_min_f32_e32 v0, 0x41e6d4ca, v136
	v_exp_f32_e32 v139, v0
	v_min_f32_e32 v0, 0x41e6d4ca, v137
	v_exp_f32_e32 v138, v0
	v_pk_add_f32 v[136:137], v[142:143], 1.0 op_sel_hi:[1,0]
	v_pk_add_f32 v[138:139], v[138:139], 1.0 op_sel_hi:[1,0]
	v_mul_f32_e32 v142, v137, v136
	v_mul_f32_e32 v143, v139, v138
	s_nop 0
	v_mul_f32_e32 v0, v142, v143
	v_rcp_f32_e32 v144, v0
	s_nop 0
	v_mul_f32_e32 v0, v143, v144
	v_mul_f32_e32 v142, v142, v144
	v_pk_mul_f32 v[144:145], v[136:137], v[0:1] op_sel_hi:[1,0]
	v_pk_mul_f32 v[136:137], v[138:139], v[142:143] op_sel_hi:[1,0]
	s_nop 0
	v_pk_mul_f32 v[136:137], v[4:5], v[136:137]
	v_pk_mul_f32 v[132:133], v[2:3], v[144:145]
	v_cvt_pk_bf16_f32 v130, v134, v135
	v_cvt_pk_bf16_f32 v131, v140, v141
	v_cvt_pk_bf16_f32 v132, v132, v133
